# K2A1 with the half-mode test hoisted: compare before the first MFMA block, branch replaces the no-op setprio pair between the two blocks
# speedup vs baseline: 1.0036x; 1.0036x over previous
.Lk0_w1:
	s_waitcnt lgkmcnt(0)
	s_barrier
	s_setprio 1
	s_waitcnt lgkmcnt(0)
	s_cmp_eq_u32 s101, 1
	v_mfma_f32_16x16x32_bf16 v[126:129], v[140:143], v[174:177], v[126:129]
	v_mfma_f32_16x16x32_bf16 v[122:125], v[150:153], v[174:177], v[122:125]
	v_mfma_f32_16x16x32_bf16 v[114:117], v[140:143], v[200:203], v[114:117]
	v_mfma_f32_16x16x32_bf16 v[106:109], v[150:153], v[200:203], v[106:109]
	v_mfma_f32_16x16x32_bf16 v[98:101], v[140:143], v[208:211], v[98:101]
	v_mfma_f32_16x16x32_bf16 v[90:93], v[150:153], v[208:211], v[90:93]
	v_mfma_f32_16x16x32_bf16 v[82:85], v[140:143], v[222:225], v[82:85]
	v_mfma_f32_16x16x32_bf16 v[72:75], v[150:153], v[222:225], v[72:75]
	v_mfma_f32_16x16x32_bf16 v[126:129], v[146:149], v[178:181], v[126:129]
	v_mfma_f32_16x16x32_bf16 v[122:125], v[154:157], v[178:181], v[122:125]
	v_mfma_f32_16x16x32_bf16 v[114:117], v[146:149], v[204:207], v[114:117]
	v_mfma_f32_16x16x32_bf16 v[106:109], v[154:157], v[204:207], v[106:109]
	v_mfma_f32_16x16x32_bf16 v[98:101], v[146:149], v[212:215], v[98:101]
	v_mfma_f32_16x16x32_bf16 v[90:93], v[154:157], v[212:215], v[90:93]
	v_mfma_f32_16x16x32_bf16 v[82:85], v[146:149], v[226:229], v[82:85]
	v_mfma_f32_16x16x32_bf16 v[72:75], v[154:157], v[226:229], v[72:75]
	s_cbranch_scc1 .Lk0_half1
	v_mfma_f32_16x16x32_bf16 v[118:121], v[158:161], v[174:177], v[118:121]
	v_mfma_f32_16x16x32_bf16 v[110:113], v[166:169], v[174:177], v[110:113]
	v_mfma_f32_16x16x32_bf16 v[102:105], v[158:161], v[200:203], v[102:105]
	v_mfma_f32_16x16x32_bf16 v[94:97], v[166:169], v[200:203], v[94:97]
	v_mfma_f32_16x16x32_bf16 v[86:89], v[158:161], v[208:211], v[86:89]
	v_mfma_f32_16x16x32_bf16 v[76:79], v[166:169], v[208:211], v[76:79]
	v_mfma_f32_16x16x32_bf16 v[68:71], v[158:161], v[222:225], v[68:71]
	v_mfma_f32_16x16x32_bf16 v[64:67], v[166:169], v[222:225], v[64:67]
	v_mfma_f32_16x16x32_bf16 v[118:121], v[162:165], v[178:181], v[118:121]
	v_mfma_f32_16x16x32_bf16 v[110:113], v[170:173], v[178:181], v[110:113]
	v_mfma_f32_16x16x32_bf16 v[102:105], v[162:165], v[204:207], v[102:105]
	v_mfma_f32_16x16x32_bf16 v[94:97], v[170:173], v[204:207], v[94:97]
	v_mfma_f32_16x16x32_bf16 v[86:89], v[162:165], v[212:215], v[86:89]
	v_mfma_f32_16x16x32_bf16 v[76:79], v[170:173], v[212:215], v[76:79]
	v_mfma_f32_16x16x32_bf16 v[68:71], v[162:165], v[226:229], v[68:71]
	v_mfma_f32_16x16x32_bf16 v[64:67], v[170:173], v[226:229], v[64:67]
.Lk0_half1:
	s_setprio 0
	s_barrier
	s_add_i32 s85, s85, s39
	v_lshl_add_u64 v[182:183], s[6:7], 0, v[80:81]
	s_mov_b32 m0, s85
	ds_read_b128 v[174:177], v145 offset:16384
	ds_read_b128 v[178:181], v145 offset:17408
	ds_read_b128 v[200:203], v145 offset:18432
	ds_read_b128 v[204:207], v145 offset:19456
	ds_read_b128 v[208:211], v145 offset:20480
	ds_read_b128 v[212:215], v145 offset:21504
	ds_read_b128 v[222:225], v145 offset:22528
	ds_read_b128 v[226:229], v145 offset:23552
	global_load_lds_dwordx4 v[182:183], off
	s_add_i32 m0, s85, 0x2000
	s_add_u32 s86, s6, 0x40000
	v_lshl_add_u64 v[184:185], s[6:7], 0, v[130:131]
	s_addc_u32 s87, s7, 0
	s_add_i32 s85, s88, s39
	global_load_lds_dwordx4 v[184:185], off
	v_lshl_add_u64 v[188:189], s[86:87], 0, v[80:81]
	s_mov_b32 m0, s85
	v_lshl_add_u64 v[190:191], s[30:31], 0, v[132:133]
	s_cmp_eq_u32 s101, 1
	s_cbranch_scc1 .Lk0_nb1a
	global_load_lds_dwordx4 v[188:189], off
	v_lshl_add_u64 v[188:189], s[86:87], 0, v[130:131]
	s_add_i32 m0, s85, 0x2000
	s_nop 0
	global_load_lds_dwordx4 v[188:189], off

.Lk0_w2:
	s_waitcnt lgkmcnt(0)
	s_barrier
	s_setprio 1
	s_waitcnt lgkmcnt(0)
	s_cmp_eq_u32 s101, 1
	v_mfma_f32_16x16x32_bf16 v[60:63], v[140:143], v[174:177], v[60:63]
	v_mfma_f32_16x16x32_bf16 v[56:59], v[150:153], v[174:177], v[56:59]
	v_mfma_f32_16x16x32_bf16 v[48:51], v[140:143], v[200:203], v[48:51]
	v_mfma_f32_16x16x32_bf16 v[40:43], v[150:153], v[200:203], v[40:43]
	v_mfma_f32_16x16x32_bf16 v[32:35], v[140:143], v[208:211], v[32:35]
	v_mfma_f32_16x16x32_bf16 v[24:27], v[150:153], v[208:211], v[24:27]
	v_mfma_f32_16x16x32_bf16 v[16:19], v[140:143], v[222:225], v[16:19]
	v_mfma_f32_16x16x32_bf16 v[8:11], v[150:153], v[222:225], v[8:11]
	v_mfma_f32_16x16x32_bf16 v[60:63], v[146:149], v[178:181], v[60:63]
	v_mfma_f32_16x16x32_bf16 v[56:59], v[154:157], v[178:181], v[56:59]
	v_mfma_f32_16x16x32_bf16 v[48:51], v[146:149], v[204:207], v[48:51]
	v_mfma_f32_16x16x32_bf16 v[40:43], v[154:157], v[204:207], v[40:43]
	v_mfma_f32_16x16x32_bf16 v[32:35], v[146:149], v[212:215], v[32:35]
	v_mfma_f32_16x16x32_bf16 v[24:27], v[154:157], v[212:215], v[24:27]
	v_mfma_f32_16x16x32_bf16 v[16:19], v[146:149], v[226:229], v[16:19]
	v_mfma_f32_16x16x32_bf16 v[8:11], v[154:157], v[226:229], v[8:11]
	s_cbranch_scc1 .Lk0_half2
	v_mfma_f32_16x16x32_bf16 v[52:55], v[158:161], v[174:177], v[52:55]
	v_mfma_f32_16x16x32_bf16 v[44:47], v[166:169], v[174:177], v[44:47]
	v_mfma_f32_16x16x32_bf16 v[36:39], v[158:161], v[200:203], v[36:39]
	v_mfma_f32_16x16x32_bf16 v[28:31], v[166:169], v[200:203], v[28:31]
	v_mfma_f32_16x16x32_bf16 v[20:23], v[158:161], v[208:211], v[20:23]
	v_mfma_f32_16x16x32_bf16 v[12:15], v[166:169], v[208:211], v[12:15]
	v_mfma_f32_16x16x32_bf16 v[4:7], v[158:161], v[222:225], v[4:7]
	v_mfma_f32_16x16x32_bf16 v[0:3], v[166:169], v[222:225], v[0:3]
	v_mfma_f32_16x16x32_bf16 v[52:55], v[162:165], v[178:181], v[52:55]
	v_mfma_f32_16x16x32_bf16 v[44:47], v[170:173], v[178:181], v[44:47]
	v_mfma_f32_16x16x32_bf16 v[36:39], v[162:165], v[204:207], v[36:39]
	v_mfma_f32_16x16x32_bf16 v[28:31], v[170:173], v[204:207], v[28:31]
	v_mfma_f32_16x16x32_bf16 v[20:23], v[162:165], v[212:215], v[20:23]
	v_mfma_f32_16x16x32_bf16 v[12:15], v[170:173], v[212:215], v[12:15]
	v_mfma_f32_16x16x32_bf16 v[4:7], v[162:165], v[226:229], v[4:7]
	v_mfma_f32_16x16x32_bf16 v[0:3], v[170:173], v[226:229], v[0:3]
.Lk0_half2:
	s_setprio 0
	s_barrier
	s_add_i32 s85, 0, 0x18000
	s_add_i32 s86, 0, 0x1c000
	v_add_u32_e32 v154, s85, v144
	v_add_u32_e32 v170, s86, v144
	ds_read_b128 v[140:143], v154
	ds_read_b128 v[146:149], v154 offset:1024
	ds_read_b128 v[150:153], v154 offset:2048
	ds_read_b128 v[154:157], v154 offset:3072
	s_cmp_eq_u32 s101, 1
	s_cbranch_scc1 .Lk0_rb2
	ds_read_b128 v[158:161], v170
	ds_read_b128 v[162:165], v170 offset:1024
	ds_read_b128 v[166:169], v170 offset:2048
	ds_read_b128 v[170:173], v170 offset:3072

.Lk0_half3:
	s_setprio 0
	s_barrier
	s_add_i32 s30, s85, s39
	v_lshl_add_u64 v[182:183], v[182:183], 0, s[12:13]
	s_mov_b32 m0, s30
	ds_read_b128 v[174:177], v145 offset:49152
	ds_read_b128 v[178:181], v145 offset:50176
	ds_read_b128 v[200:203], v145 offset:51200
	ds_read_b128 v[204:207], v145 offset:52224
	ds_read_b128 v[208:211], v145 offset:53248
	ds_read_b128 v[212:215], v145 offset:54272
	ds_read_b128 v[222:225], v145 offset:55296
	ds_read_b128 v[226:229], v145 offset:56320
	global_load_lds_dwordx4 v[182:183], off
	s_add_i32 m0, s30, 0x2000
	s_add_u32 s6, s6, 0x40080
	v_lshl_add_u64 v[182:183], v[184:185], 0, s[12:13]
	s_addc_u32 s7, s7, 0
	s_add_i32 s30, s86, s39
	global_load_lds_dwordx4 v[182:183], off
	s_cmp_eq_u32 s101, 1
	s_cbranch_scc1 .Lk0_nb1b
	v_lshl_add_u64 v[182:183], s[6:7], 0, v[80:81]
	s_mov_b32 m0, s30
	s_nop 0
	global_load_lds_dwordx4 v[182:183], off
	v_lshl_add_u64 v[182:183], s[6:7], 0, v[130:131]
	s_add_i32 m0, s30, 0x2000
	s_nop 0
	global_load_lds_dwordx4 v[182:183], off

.Lk0_half4:
	s_setprio 0
	s_barrier
	s_add_i32 s84, s84, 2
	s_add_u32 s82, s82, 0x100
	s_addc_u32 s83, s83, 0
	s_add_u32 s0, s0, 0x100
	s_addc_u32 s1, s1, 0
	s_cmp_gt_u32 s84, 13
	s_cbranch_scc0 .LBB0_477
	s_and_b64 vcc, exec, s[10:11]
	s_cbranch_vccz .LBB0_480
	s_barrier
